# G1 unit loop: glrp partial loads of unit k+1 issued at the top of unit k into spare VGPRs (copied at the next unit top); unit-top vmcnt waits dropped for units 1-3
# baseline (speedup 1.0000x reference)
.LBB0_1090:
	s_or_b32 s8, s87, s81
	s_bfe_i32 s0, s8, 0x1e0000
	s_ashr_i32 s1, s0, 31
	s_lshl_b64 s[10:11], s[0:1], 12
	v_lshl_add_u64 v[66:67], v[116:117], 0, s[10:11]
	v_add_co_u32_e32 v68, vcc, s33, v66
	s_lshl_b64 s[0:1], s[0:1], 17
	s_nop 0
	v_addc_co_u32_e32 v69, vcc, 0, v67, vcc
	v_add_co_u32_e32 v70, vcc, s55, v66
	v_mov_b32_e32 v124, v0
	s_nop 0
	v_addc_co_u32_e32 v71, vcc, 0, v67, vcc
	v_add_co_u32_e32 v72, vcc, s70, v66
	s_nop 1
	v_addc_co_u32_e32 v73, vcc, 0, v67, vcc
	s_mov_b32 s100, 0x1000
	s_mov_b32 s101, 0
	s_cmp_eq_u32 s87, 0
	s_cbranch_scc0 .Lg1_copy
	global_load_dword v98, v[66:67], off
	global_load_dword v99, v[68:69], off
	global_load_dword v100, v[70:71], off
	global_load_dword v101, v[72:73], off
	global_load_dword v102, v[72:73], off offset:2048
	global_load_dword v103, v[70:71], off offset:2048
	global_load_dword v104, v[68:69], off offset:2048
	global_load_dword v105, v[66:67], off offset:2048
	s_branch .Lg1_n8
.Lg1_copy:
	v_mov_b32_e32 v98, v190
	v_mov_b32_e32 v99, v191
	v_mov_b32_e32 v100, v192
	v_mov_b32_e32 v101, v193
	v_mov_b32_e32 v102, v194
	v_mov_b32_e32 v103, v195
	v_mov_b32_e32 v104, v196
	v_mov_b32_e32 v105, v197
	s_cmp_eq_u32 s87, 3
	s_cbranch_scc1 .Lg1_x4
.Lg1_n8:
	v_lshl_add_u64 v[204:205], v[66:67], 0, s[100:101]
	v_lshl_add_u64 v[206:207], v[68:69], 0, s[100:101]
	v_lshl_add_u64 v[208:209], v[70:71], 0, s[100:101]
	v_lshl_add_u64 v[210:211], v[72:73], 0, s[100:101]
	global_load_dword v190, v[204:205], off
	global_load_dword v191, v[206:207], off
	global_load_dword v192, v[208:209], off
	global_load_dword v193, v[210:211], off
	global_load_dword v194, v[210:211], off offset:2048
	global_load_dword v195, v[208:209], off offset:2048
	global_load_dword v196, v[206:207], off offset:2048
	global_load_dword v197, v[204:205], off offset:2048
.Lg1_x4:
	v_lshl_or_b32 v66, v118, 1, s0
	v_mov_b32_e32 v67, s1
	v_lshl_add_u64 v[68:69], v[120:121], 0, v[66:67]
	v_lshl_add_u64 v[70:71], v[122:123], 0, v[66:67]
	global_load_dwordx4 v[94:97], v[68:69], off
	global_load_dwordx4 v[90:93], v[68:69], off offset:1024
	global_load_dwordx4 v[86:89], v[68:69], off offset:2048
	global_load_dwordx4 v[82:85], v[68:69], off offset:3072
	global_load_dwordx4 v[74:77], v[70:71], off
	s_nop 0
	global_load_dwordx4 v[66:69], v[70:71], off offset:256
	global_load_dwordx4 v[78:81], v[70:71], off offset:2048
	s_nop 0
	global_load_dwordx4 v[70:73], v[70:71], off offset:2304
	s_cmp_lg_u32 s87, 0
	s_cbranch_scc1 .Lg1_nowait
	s_waitcnt vmcnt(16)
.Lg1_nowait:
	v_add_f32_e32 v98, v98, v99
	v_readfirstlane_b32 s17, v124
	v_add_f32_e32 v99, v100, v101
	v_lshl_add_u32 v106, v124, 2, 0
	v_add_f32_e32 v101, v103, v102
	v_ashrrev_i32_e32 v125, 31, v124
	v_add_f32_e32 v100, v105, v104
	v_cmp_gt_i32_e32 vcc, s54, v124
	v_add_f32_e32 v98, v98, v99
	v_add_f32_e32 v99, v100, v101
	v_lshl_add_u32 v157, v124, 2, 0
	ds_write2st64_b32 v106, v149, v150 offset0:224 offset1:232
	ds_write2st64_b32 v106, v151, v152 offset0:240 offset1:248
	ds_write2st64_b32 v106, v98, v99 offset0:208 offset1:216
	s_and_saveexec_b64 s[0:1], vcc
	v_add_u32_e32 v98, 0x10000, v157
	ds_write_b32 v98, v153
	s_or_b64 exec, exec, s[0:1]
	v_and_b32_e32 v98, 0x7f, v124
	v_lshlrev_b32_e32 v114, 2, v98
	v_add_u32_e32 v126, 0, v114
	s_waitcnt lgkmcnt(0)
	s_barrier
	ds_read2st64_b32 v[98:99], v126 offset0:224 offset1:226
	ds_read2st64_b32 v[100:101], v126 offset0:228 offset1:230
	ds_read2st64_b32 v[102:103], v126 offset0:232 offset1:234
	ds_read2st64_b32 v[104:105], v126 offset0:236 offset1:238
	ds_read2st64_b32 v[106:107], v126 offset0:240 offset1:242
	ds_read2st64_b32 v[108:109], v126 offset0:244 offset1:246
	ds_read2st64_b32 v[110:111], v126 offset0:248 offset1:250
	ds_read2st64_b32 v[112:113], v126 offset0:252 offset1:254
	v_add_u32_e32 v126, 0x10000, v126
	ds_read_b32 v128, v126
	v_ashrrev_i32_e32 v126, 3, v124
	v_lshrrev_b32_e32 v129, 4, v126
	v_mad_u64_u32 v[126:127], s[0:1], v129, s71, v[114:115]
	s_lshl_b32 s8, s8, 2
	v_lshl_add_u32 v127, v129, 10, v154
	v_mov_b32_e32 v114, 0
	s_mov_b32 s9, 16
